# final RMSNorm loop: loop-invariant gain loads and output-pointer scalar load hoisted out of the row loop (no dependent load round trips per row)
# speedup vs baseline: 1.0033x; 1.0033x over previous
.LBB0_1280:
	v_readlane_b32 s3, v253, 2
	v_readfirstlane_b32 s2, v196
	s_ashr_i32 s2, s2, 6
	s_add_i32 s2, s2, s3
	s_mov_b32 s4, 25
	s_cmpk_gt_i32 s2, 0x7fff
	s_cbranch_scc1 .LBB0_1283
	s_ashr_i32 s5, s4, 31
	s_lshl_b64 s[4:5], s[4:5], 3
	s_add_u32 s4, s0, s4
	s_addc_u32 s5, s1, s5
	s_load_dwordx2 s[4:5], s[4:5], 0x0
	v_lshlrev_b32_e32 v0, 4, v196
	v_mov_b32_e32 v1, 0
	v_and_b32_e32 v0, 0x3f0, v0
	s_ashr_i32 s3, s2, 31
	s_waitcnt lgkmcnt(0)
	v_lshl_add_u64 v[0:1], s[4:5], 0, v[0:1]
	s_lshl_b64 s[4:5], s[2:3], 12
	v_and_b32_e32 v2, 63, v196
	s_ashr_i32 s21, s20, 31
	v_and_b32_e32 v4, 64, v197
	v_lshl_or_b32 v2, v2, 4, s4
	v_mov_b32_e32 v3, s5
	s_lshl_b64 s[4:5], s[20:21], 12
	v_add_u32_e32 v4, 64, v4
	v_xor_b32_e32 v5, 1, v197
	v_xor_b32_e32 v6, 2, v197
	v_xor_b32_e32 v7, 4, v197
	v_xor_b32_e32 v8, 8, v197
	v_xor_b32_e32 v9, 16, v197
	v_xor_b32_e32 v10, 32, v197
	v_mov_b32_e32 v11, 0x358637bd
	s_load_dwordx2 s[6:7], s[0:1], 0xd0
	global_load_dwordx4 v[60:63], v[0:1], off
	global_load_dwordx4 v[64:67], v[0:1], off offset:1024
	global_load_dwordx4 v[68:71], v[0:1], off offset:2048
	global_load_dwordx4 v[72:75], v[0:1], off offset:3072
	s_waitcnt lgkmcnt(0)
.LBB0_1282:
	v_cmp_lt_i32_e32 vcc, v5, v4
	s_add_i32 s2, s2, s20
	s_cmp_lt_i32 s2, 0x8000
	v_cndmask_b32_e32 v34, v197, v5, vcc
	v_lshl_add_u64 v[32:33], s[6:7], 0, v[2:3]
	global_load_dwordx4 v[12:15], v[32:33], off
	global_load_dwordx4 v[16:19], v[32:33], off offset:1024
	global_load_dwordx4 v[20:23], v[32:33], off offset:2048
	global_load_dwordx4 v[24:27], v[32:33], off offset:3072
	v_cmp_lt_i32_e32 vcc, v6, v4
	v_lshlrev_b32_e32 v45, 2, v34
	v_lshl_add_u64 v[2:3], v[2:3], 0, s[4:5]
	v_cndmask_b32_e32 v35, v197, v6, vcc
	v_cmp_lt_i32_e32 vcc, v7, v4
	v_lshlrev_b32_e32 v48, 2, v35
	s_waitcnt vmcnt(3)
	v_pk_mul_f32 v[34:35], v[14:15], v[14:15]
	v_cndmask_b32_e32 v36, v197, v7, vcc
	v_cmp_lt_i32_e32 vcc, v8, v4
	v_lshlrev_b32_e32 v49, 2, v36
	s_waitcnt vmcnt(2)
	v_pk_mul_f32 v[40:41], v[16:17], v[16:17]
	v_cndmask_b32_e32 v37, v197, v8, vcc
	v_cmp_lt_i32_e32 vcc, v9, v4
	v_lshlrev_b32_e32 v50, 2, v37
	v_pk_mul_f32 v[36:37], v[12:13], v[12:13]
	v_cndmask_b32_e32 v38, v197, v9, vcc
	v_cmp_lt_i32_e32 vcc, v10, v4
	v_lshlrev_b32_e32 v51, 2, v38
	v_pk_mov_b32 v[46:47], v[36:37], v[34:35] op_sel:[1,0]
	v_cndmask_b32_e32 v39, v197, v10, vcc
	v_lshlrev_b32_e32 v52, 2, v39
	v_pk_mul_f32 v[38:39], v[18:19], v[18:19]
	v_mov_b32_e32 v37, v35
	v_pk_mov_b32 v[34:35], v[40:41], v[38:39] op_sel:[1,0]
	v_mov_b32_e32 v41, v39
	s_waitcnt vmcnt(1)
	v_mul_f32_e32 v42, v21, v21
	v_mul_f32_e32 v44, v23, v23
	v_pk_add_f32 v[36:37], v[46:47], v[36:37]
	v_pk_add_f32 v[34:35], v[34:35], v[40:41]
	s_waitcnt vmcnt(0)
	v_mul_f32_e32 v53, v24, v24
	v_mul_f32_e32 v54, v25, v25
	v_mul_f32_e32 v55, v26, v26
	v_mul_f32_e32 v56, v27, v27
	v_pk_fma_f32 v[38:39], v[20:21], v[20:21], v[42:43] op_sel_hi:[1,1,0]
	v_pk_fma_f32 v[42:43], v[22:23], v[22:23], v[44:45] op_sel_hi:[1,1,0]
	v_pk_add_f32 v[36:37], v[36:37], v[36:37] op_sel:[0,1] op_sel_hi:[1,0]
	v_pk_add_f32 v[34:35], v[34:35], v[34:35] op_sel:[0,1] op_sel_hi:[1,0]
	v_mov_b32_e32 v39, v55
	v_mov_b32_e32 v43, v56
	v_mov_b32_e32 v37, v53
	v_mov_b32_e32 v35, v54
	v_pk_add_f32 v[38:39], v[38:39], v[42:43]
	v_pk_add_f32 v[34:35], v[36:37], v[34:35]
	s_nop 0
	v_pk_add_f32 v[34:35], v[34:35], v[38:39]
	s_nop 0
	v_add_f32_e32 v34, v34, v35
	ds_bpermute_b32 v35, v45, v34
	s_waitcnt lgkmcnt(0)
	v_add_f32_e32 v34, v34, v35
	ds_bpermute_b32 v35, v48, v34
	s_waitcnt lgkmcnt(0)
	v_add_f32_e32 v34, v34, v35
	ds_bpermute_b32 v35, v49, v34
	s_waitcnt lgkmcnt(0)
	v_add_f32_e32 v34, v34, v35
	ds_bpermute_b32 v35, v50, v34
	s_waitcnt lgkmcnt(0)
	v_add_f32_e32 v34, v34, v35
	ds_bpermute_b32 v35, v51, v34
	s_waitcnt lgkmcnt(0)
	v_add_f32_e32 v34, v34, v35
	ds_bpermute_b32 v35, v52, v34
	s_waitcnt lgkmcnt(0)
	v_add_f32_e32 v34, v34, v35
	v_fmamk_f32 v34, v34, 0x3a800000, v11
	v_rsq_f32_e32 v34, v34
	s_nop 0
	v_pk_mul_f32 v[12:13], v[12:13], v[34:35] op_sel_hi:[1,0]
	v_pk_mul_f32 v[14:15], v[14:15], v[34:35] op_sel_hi:[1,0]
	v_pk_mul_f32 v[12:13], v[60:61], v[12:13]
	v_pk_mul_f32 v[14:15], v[62:63], v[14:15]
	global_store_dwordx4 v[32:33], v[12:15], off
	v_pk_mul_f32 v[18:19], v[18:19], v[34:35] op_sel_hi:[1,0]
	v_pk_mul_f32 v[16:17], v[16:17], v[34:35] op_sel_hi:[1,0]
	v_pk_mul_f32 v[14:15], v[66:67], v[18:19]
	v_pk_mul_f32 v[12:13], v[64:65], v[16:17]
	global_store_dwordx4 v[32:33], v[12:15], off offset:1024
	v_pk_mul_f32 v[16:17], v[22:23], v[34:35] op_sel_hi:[1,0]
	v_pk_mul_f32 v[18:19], v[20:21], v[34:35] op_sel_hi:[1,0]
	v_pk_mul_f32 v[14:15], v[70:71], v[16:17]
	v_pk_mul_f32 v[12:13], v[68:69], v[18:19]
	global_store_dwordx4 v[32:33], v[12:15], off offset:2048
	v_pk_mul_f32 v[16:17], v[26:27], v[34:35] op_sel_hi:[1,0]
	v_pk_mul_f32 v[18:19], v[24:25], v[34:35] op_sel_hi:[1,0]
	v_pk_mul_f32 v[14:15], v[74:75], v[16:17]
	v_pk_mul_f32 v[12:13], v[72:73], v[18:19]
	global_store_dwordx4 v[32:33], v[12:15], off offset:3072
	s_cbranch_scc1 .LBB0_1282
